# safe2 + attention pass-1 epilogue row reductions: xor 1/2/4/8 steps via DPP adds instead of ds_bpermute round trips (20 of 32 sites)
# speedup vs baseline: 1.0008x; 1.0008x over previous
; __device__ __forceinline__ unsigned cvtpk(float lo, float hi) { unsigned r; asm volatile("v_cvt_pk_bf16_f32 %0, %1, %2" : "=v"(r) : "v"(lo), "v"(hi)); return r; }
; template <bool GRPB> __device__ __forceinline__ void attn_pass(const float mbK, const float bmax2, const int pass, float* __restrict__ scr, bf16* __restrict__ mixrow, const float lam, const float* __restrict__ gsub, const float one_m_li, ...
;     ...
;     float g[4];
;     const float lam_ = *(const float*)(lds + 147328), oml_ = *(const float*)(lds + 147332);
; #pragma unroll
;     for (int d0 = 0; d0 < 4; ++d0) g[d0] = gsub[d0 * 32 + r32] * oml_;
; #pragma unroll
;     for (int r4 = 0; r4 < 4; ++r4) { const f32x4 lv = *(const f32x4*)(li_e + 8 * r4 + 4 * hi);
;       f32x4 av[4];
; #pragma unroll
;       for (int d0 = 0; d0 < 4; ++d0) av[d0] = scr4[d0 * 4 + r4];
; #pragma unroll
;       for (int i = 0; i < 4; ++i) { const float rl = __builtin_amdgcn_rcpf(lv[i]) * lam_; float dv[4]; float sq = 0.f;
; #pragma unroll
;         for (int d0 = 0; d0 < 4; ++d0) { dv[d0] = av[d0][i] - rl * o[d0][4 * r4 + i]; sq += dv[d0] * dv[d0]; }
;         sq += __shfl_xor(sq, 1); sq += __shfl_xor(sq, 2); sq += __shfl_xor(sq, 4); sq += __shfl_xor(sq, 8); sq += __shfl_xor(sq, 16);
;         const float rs = __builtin_amdgcn_rsqf(sq * (1.0f / 128.0f) + EPS);
;         unsigned short* orow = (unsigned short*)(ost_e + (8 * r4 + 4 * hi + i) * OST_PITCH) + r32;
; #pragma unroll
;         for (int d0 = 0; d0 < 4; ++d0) orow[d0 * 32] = (unsigned short)(cvtpk(dv[d0] * rs * g[d0], 0.f) & 0xffffu); } }
.LBB0_248:
	s_or_b64 exec, exec, s[0:1]
	v_lshrrev_b32_e32 v64, 6, v67
	s_movk_i32 s0, 0x2200
	v_mul_lo_u32 v88, v64, s0
	v_readlane_b32 s0, v254, 41
	v_ashrrev_i32_e32 v147, 31, v146
	v_lshlrev_b64 v[64:65], 8, v[146:147]
	v_add_u32_e32 v93, s0, v88
	v_readlane_b32 s0, v254, 37
	s_waitcnt lgkmcnt(0)
	v_lshl_add_u64 v[86:87], s[40:41], 0, v[64:65]
	v_add_u32_e32 v92, v66, v180
	v_mov_b32_e32 v64, s0
	ds_read_b64 v[84:85], v64
	ds_read_b128 v[80:83], v92
	v_lshlrev_b32_e32 v64, 2, v181
	global_load_dword v168, v64, s[42:43]
	global_load_dword v169, v64, s[42:43] offset:128
	global_load_dword v170, v64, s[42:43] offset:256
	global_load_dword v171, v64, s[42:43] offset:384
	v_lshlrev_b32_e32 v94, 1, v181
	s_waitcnt lgkmcnt(0)
	v_rcp_f32_e32 v80, v80
	s_nop 0
	v_mul_f32_e32 v80, v84, v80
	s_waitcnt vmcnt(0)
	v_mul_f32_e32 v89, v85, v168
	v_mul_f32_e32 v90, v85, v169
	v_mul_f32_e32 v91, v85, v170
	v_mul_f32_e32 v85, v85, v171
	global_load_dwordx4 v[76:79], v[86:87], off
	global_load_dwordx4 v[72:75], v[86:87], off offset:64
	global_load_dwordx4 v[68:71], v[86:87], off offset:128
	global_load_dwordx4 v[64:67], v[86:87], off offset:192
	global_load_dwordx4 v[96:99], v[86:87], off offset:16
	global_load_dwordx4 v[100:103], v[86:87], off offset:80
	global_load_dwordx4 v[104:107], v[86:87], off offset:144
	global_load_dwordx4 v[108:111], v[86:87], off offset:208
	global_load_dwordx4 v[112:115], v[86:87], off offset:32
	global_load_dwordx4 v[116:119], v[86:87], off offset:96
	global_load_dwordx4 v[120:123], v[86:87], off offset:160
	global_load_dwordx4 v[124:127], v[86:87], off offset:224
	global_load_dwordx4 v[128:131], v[86:87], off offset:48
	global_load_dwordx4 v[132:135], v[86:87], off offset:112
	global_load_dwordx4 v[136:139], v[86:87], off offset:176
	global_load_dwordx4 v[140:143], v[86:87], off offset:240
	s_waitcnt vmcnt(15)
	v_fma_f32 v0, -v0, v80, v76
	s_waitcnt vmcnt(14)
	v_fma_f32 v16, -v16, v80, v72
	v_mul_f32_e32 v72, v16, v16
	v_fmac_f32_e32 v72, v0, v0
	s_waitcnt vmcnt(13)
	v_fma_f32 v32, -v32, v80, v68
	v_fmac_f32_e32 v72, v32, v32
	s_waitcnt vmcnt(12)
	v_fma_f32 v48, -v48, v80, v64
	v_fmac_f32_e32 v72, v48, v48
	s_nop 1
	v_add_f32_dpp v64, v72, v72 quad_perm:[1,0,3,2] row_mask:0xf bank_mask:0xf
	s_nop 1
	v_add_f32_dpp v64, v64, v64 quad_perm:[2,3,0,1] row_mask:0xf bank_mask:0xf
	s_nop 1
	v_add_f32_dpp v64, v64, v64 row_half_mirror row_mask:0xf bank_mask:0xf
	s_nop 1
	v_add_f32_dpp v64, v64, v64 row_mirror row_mask:0xf bank_mask:0xf
	ds_bpermute_b32 v68, v213, v64
	s_waitcnt lgkmcnt(0)
	v_add_f32_e32 v64, v64, v68
	v_fmamk_f32 v64, v64, 0x3c000000, v233
	v_rsq_f32_e32 v64, v64
	v_mul_u32_u24_e32 v68, 0x440, v190
	v_add3_u32 v68, v93, v94, v68
	v_mul_f32_e32 v0, v0, v64
	v_mul_f32_e32 v0, v89, v0
	v_cvt_pk_bf16_f32 v0, v0, v144
	ds_write_b16 v68, v0
	v_mul_f32_e32 v0, v16, v64
	v_mul_f32_e32 v0, v90, v0
	v_cvt_pk_bf16_f32 v0, v0, v144
	ds_write_b16 v68, v0 offset:64
	v_mul_f32_e32 v0, v32, v64
	v_mul_f32_e32 v0, v91, v0
	v_cvt_pk_bf16_f32 v0, v0, v144
	ds_write_b16 v68, v0 offset:128
	v_mul_f32_e32 v0, v48, v64
	v_mul_f32_e32 v0, v85, v0
	v_cvt_pk_bf16_f32 v0, v0, v144
	ds_write_b16 v68, v0 offset:192
	v_rcp_f32_e32 v0, v81
	s_nop 0
	v_mul_f32_e32 v0, v84, v0
	v_fma_f32 v16, -v17, v0, v73
	v_fma_f32 v1, -v1, v0, v77
	v_mul_f32_e32 v17, v16, v16
	v_fmac_f32_e32 v17, v1, v1
	v_fma_f32 v32, -v33, v0, v69
	v_fmac_f32_e32 v17, v32, v32
	v_fma_f32 v0, -v49, v0, v65
	v_fmac_f32_e32 v17, v0, v0
	ds_bpermute_b32 v33, v145, v17
	s_waitcnt lgkmcnt(0)
	v_add_f32_e32 v17, v17, v33
	ds_bpermute_b32 v33, v210, v17
	s_waitcnt lgkmcnt(0)
	v_add_f32_e32 v17, v17, v33
	ds_bpermute_b32 v33, v211, v17
	s_waitcnt lgkmcnt(0)
	v_add_f32_e32 v17, v17, v33
	ds_bpermute_b32 v33, v212, v17
	s_waitcnt lgkmcnt(0)
	v_add_f32_e32 v17, v17, v33
	ds_bpermute_b32 v33, v213, v17
	s_waitcnt lgkmcnt(0)
	v_add_f32_e32 v17, v17, v33
	v_fmamk_f32 v17, v17, 0x3c000000, v233
	v_rsq_f32_e32 v17, v17
	s_nop 0
	v_mul_f32_e32 v1, v1, v17
	v_mul_f32_e32 v1, v89, v1
	v_cvt_pk_bf16_f32 v1, v1, v144
	ds_write_b16 v68, v1 offset:272
	v_mul_f32_e32 v1, v16, v17
	v_mul_f32_e32 v1, v90, v1
	v_cvt_pk_bf16_f32 v1, v1, v144
	ds_write_b16 v68, v1 offset:336
	v_mul_f32_e32 v1, v32, v17
	v_mul_f32_e32 v0, v0, v17
	v_mul_f32_e32 v1, v91, v1
	v_mul_f32_e32 v0, v85, v0
	v_cvt_pk_bf16_f32 v1, v1, v144
	ds_write_b16 v68, v1 offset:400
	v_cvt_pk_bf16_f32 v0, v0, v144
	ds_write_b16 v68, v0 offset:464
	v_rcp_f32_e32 v0, v82
	s_nop 0
	v_mul_f32_e32 v0, v84, v0
	v_fma_f32 v1, -v2, v0, v78
	v_fma_f32 v2, -v18, v0, v74
	v_mul_f32_e32 v16, v2, v2
	v_fmac_f32_e32 v16, v1, v1
	v_fma_f32 v17, -v34, v0, v70
	v_fmac_f32_e32 v16, v17, v17
	v_fma_f32 v0, -v50, v0, v66
	v_fmac_f32_e32 v16, v0, v0
	ds_bpermute_b32 v18, v145, v16
	s_waitcnt lgkmcnt(0)
	v_add_f32_e32 v16, v16, v18
	ds_bpermute_b32 v18, v210, v16
	s_waitcnt lgkmcnt(0)
	v_add_f32_e32 v16, v16, v18
	ds_bpermute_b32 v18, v211, v16
	s_waitcnt lgkmcnt(0)
	v_add_f32_e32 v16, v16, v18
	ds_bpermute_b32 v18, v212, v16
	s_waitcnt lgkmcnt(0)
	v_add_f32_e32 v16, v16, v18
	ds_bpermute_b32 v18, v213, v16
	s_waitcnt lgkmcnt(0)
	v_add_f32_e32 v16, v16, v18
	v_fmamk_f32 v16, v16, 0x3c000000, v233
	v_rsq_f32_e32 v16, v16
	s_nop 0
	v_mul_f32_e32 v1, v1, v16
	v_mul_f32_e32 v1, v89, v1
	v_cvt_pk_bf16_f32 v1, v1, v144
	ds_write_b16 v68, v1 offset:544
	v_mul_f32_e32 v1, v2, v16
	v_mul_f32_e32 v1, v90, v1
	v_cvt_pk_bf16_f32 v1, v1, v144
	ds_write_b16 v68, v1 offset:608
	v_mul_f32_e32 v1, v17, v16
	v_mul_f32_e32 v0, v0, v16
	v_mul_f32_e32 v1, v91, v1
	v_mul_f32_e32 v0, v85, v0
	v_cvt_pk_bf16_f32 v1, v1, v144
	ds_write_b16 v68, v1 offset:672
	v_cvt_pk_bf16_f32 v0, v0, v144
	ds_write_b16 v68, v0 offset:736
	v_rcp_f32_e32 v0, v83
	s_nop 0
	v_mul_f32_e32 v0, v84, v0
	v_fma_f32 v2, -v19, v0, v75
	v_fma_f32 v1, -v3, v0, v79
	v_mul_f32_e32 v3, v2, v2
	v_fmac_f32_e32 v3, v1, v1
	v_fma_f32 v16, -v35, v0, v71
	v_fmac_f32_e32 v3, v16, v16
	v_fma_f32 v0, -v51, v0, v67
	v_fmac_f32_e32 v3, v0, v0
	ds_bpermute_b32 v17, v145, v3
	s_waitcnt lgkmcnt(0)
; __device__ __forceinline__ unsigned cvtpk(float lo, float hi) { unsigned r; asm volatile("v_cvt_pk_bf16_f32 %0, %1, %2" : "=v"(r) : "v"(lo), "v"(hi)); return r; }
; template <bool GRPB> __device__ __forceinline__ void attn_pass(const float mbK, const float bmax2, const int pass, float* __restrict__ scr, bf16* __restrict__ mixrow, const float lam, const float* __restrict__ gsub, const float one_m_li, ...
;     ...
;       for (int i = 0; i < 4; ++i) { const float rl = __builtin_amdgcn_rcpf(lv[i]) * lam_; float dv[4]; float sq = 0.f;
; #pragma unroll
;         for (int d0 = 0; d0 < 4; ++d0) { dv[d0] = av[d0][i] - rl * o[d0][4 * r4 + i]; sq += dv[d0] * dv[d0]; }
;         sq += __shfl_xor(sq, 1); sq += __shfl_xor(sq, 2); sq += __shfl_xor(sq, 4); sq += __shfl_xor(sq, 8); sq += __shfl_xor(sq, 16);
;         const float rs = __builtin_amdgcn_rsqf(sq * (1.0f / 128.0f) + EPS);
;         unsigned short* orow = (unsigned short*)(ost_e + (8 * r4 + 4 * hi + i) * OST_PITCH) + r32;
; #pragma unroll
;         for (int d0 = 0; d0 < 4; ++d0) orow[d0 * 32] = (unsigned short)(cvtpk(dv[d0] * rs * g[d0], 0.f) & 0xffffu); } }
	v_add_f32_e32 v3, v3, v17
	ds_bpermute_b32 v17, v210, v3
	s_waitcnt lgkmcnt(0)
	v_add_f32_e32 v3, v3, v17
	ds_bpermute_b32 v17, v211, v3
	s_waitcnt lgkmcnt(0)
	v_add_f32_e32 v3, v3, v17
	ds_bpermute_b32 v17, v212, v3
	s_waitcnt lgkmcnt(0)
	v_add_f32_e32 v3, v3, v17
	ds_bpermute_b32 v17, v213, v3
	s_waitcnt lgkmcnt(0)
	v_add_f32_e32 v3, v3, v17
	v_fmamk_f32 v3, v3, 0x3c000000, v233
	v_rsq_f32_e32 v3, v3
	s_nop 0
	v_mul_f32_e32 v1, v1, v3
	v_mul_f32_e32 v1, v89, v1
	v_cvt_pk_bf16_f32 v1, v1, v144
	ds_write_b16 v68, v1 offset:816
	v_mul_f32_e32 v1, v2, v3
	v_mul_f32_e32 v1, v90, v1
	v_cvt_pk_bf16_f32 v1, v1, v144
	ds_write_b16 v68, v1 offset:880
	v_mul_f32_e32 v1, v16, v3
	v_mul_f32_e32 v0, v0, v3
	v_mul_f32_e32 v1, v91, v1
	v_mul_f32_e32 v0, v85, v0
	v_cvt_pk_bf16_f32 v1, v1, v144
	ds_write_b16 v68, v1 offset:944
	v_cvt_pk_bf16_f32 v0, v0, v144
	ds_write_b16 v68, v0 offset:1008
	ds_read_b128 v[64:67], v92 offset:32
	s_waitcnt lgkmcnt(0)
	v_rcp_f32_e32 v64, v64
	s_nop 0
	v_mul_f32_e32 v64, v84, v64
	s_waitcnt vmcnt(11)
	v_fma_f32 v4, -v4, v64, v96
	s_waitcnt vmcnt(10)
	v_fma_f32 v20, -v20, v64, v100
	v_mul_f32_e32 v32, v20, v20
	v_fmac_f32_e32 v32, v4, v4
	s_waitcnt vmcnt(9)
	v_fma_f32 v16, -v36, v64, v104
	v_fmac_f32_e32 v32, v16, v16
	s_waitcnt vmcnt(8)
	v_fma_f32 v0, -v52, v64, v108
	v_fmac_f32_e32 v32, v0, v0
	ds_bpermute_b32 v36, v145, v32
	s_waitcnt lgkmcnt(0)
	v_add_f32_e32 v32, v32, v36
	ds_bpermute_b32 v36, v210, v32
	s_waitcnt lgkmcnt(0)
	v_add_f32_e32 v32, v32, v36
	ds_bpermute_b32 v36, v211, v32
	s_waitcnt lgkmcnt(0)
	v_add_f32_e32 v32, v32, v36
	ds_bpermute_b32 v36, v212, v32
	s_waitcnt lgkmcnt(0)
	v_add_f32_e32 v32, v32, v36
	ds_bpermute_b32 v36, v213, v32
	s_waitcnt lgkmcnt(0)
	v_add_f32_e32 v32, v32, v36
	v_fmamk_f32 v32, v32, 0x3c000000, v233
	v_rsq_f32_e32 v32, v32
	s_nop 0
	v_mul_f32_e32 v4, v4, v32
	v_mul_f32_e32 v4, v89, v4
	v_cvt_pk_bf16_f32 v4, v4, v144
	ds_write_b16 v68, v4 offset:2176
	v_mul_f32_e32 v4, v20, v32
	v_mul_f32_e32 v4, v90, v4
	v_cvt_pk_bf16_f32 v4, v4, v144
	ds_write_b16 v68, v4 offset:2240
	v_mul_f32_e32 v4, v16, v32
	v_mul_f32_e32 v0, v0, v32
	v_mul_f32_e32 v4, v91, v4
	v_mul_f32_e32 v0, v85, v0
	v_cvt_pk_bf16_f32 v4, v4, v144
	ds_write_b16 v68, v4 offset:2304
	v_cvt_pk_bf16_f32 v0, v0, v144
	ds_write_b16 v68, v0 offset:2368
	v_rcp_f32_e32 v0, v65
	s_nop 0
	v_mul_f32_e32 v0, v84, v0
	v_fma_f32 v4, -v5, v0, v97
	v_fma_f32 v5, -v21, v0, v101
	v_mul_f32_e32 v16, v5, v5
	v_fmac_f32_e32 v16, v4, v4
	v_fma_f32 v17, -v37, v0, v105
	v_fmac_f32_e32 v16, v17, v17
	v_fma_f32 v0, -v53, v0, v109
	v_fmac_f32_e32 v16, v0, v0
	s_nop 1
	v_add_f32_dpp v1, v16, v16 quad_perm:[1,0,3,2] row_mask:0xf bank_mask:0xf
	s_nop 1
	v_add_f32_dpp v1, v1, v1 quad_perm:[2,3,0,1] row_mask:0xf bank_mask:0xf
	s_nop 1
	v_add_f32_dpp v1, v1, v1 row_half_mirror row_mask:0xf bank_mask:0xf
	s_nop 1
	v_add_f32_dpp v1, v1, v1 row_mirror row_mask:0xf bank_mask:0xf
	ds_bpermute_b32 v16, v213, v1
	s_waitcnt lgkmcnt(0)
	v_add_f32_e32 v1, v1, v16
	v_fmamk_f32 v1, v1, 0x3c000000, v233
	v_rsq_f32_e32 v1, v1
	s_nop 0
	v_mul_f32_e32 v4, v4, v1
	v_mul_f32_e32 v4, v89, v4
	v_cvt_pk_bf16_f32 v4, v4, v144
	ds_write_b16 v68, v4 offset:2448
	v_mul_f32_e32 v4, v5, v1
	v_mul_f32_e32 v4, v90, v4
	v_cvt_pk_bf16_f32 v4, v4, v144
	ds_write_b16 v68, v4 offset:2512
	v_mul_f32_e32 v4, v17, v1
	v_mul_f32_e32 v0, v0, v1
	v_mul_f32_e32 v4, v91, v4
	v_mul_f32_e32 v0, v85, v0
	v_cvt_pk_bf16_f32 v4, v4, v144
	ds_write_b16 v68, v4 offset:2576
	v_cvt_pk_bf16_f32 v0, v0, v144
	ds_write_b16 v68, v0 offset:2640
	v_rcp_f32_e32 v0, v66
	s_nop 0
	v_mul_f32_e32 v0, v84, v0
	v_fma_f32 v4, -v22, v0, v102
	v_fma_f32 v1, -v6, v0, v98
	v_mul_f32_e32 v5, v4, v4
	v_fmac_f32_e32 v5, v1, v1
	v_fma_f32 v6, -v38, v0, v106
	v_fmac_f32_e32 v5, v6, v6
	v_fma_f32 v0, -v54, v0, v110
	v_fmac_f32_e32 v5, v0, v0
	s_nop 1
	v_add_f32_dpp v2, v5, v5 quad_perm:[1,0,3,2] row_mask:0xf bank_mask:0xf
	s_nop 1
	v_add_f32_dpp v2, v2, v2 quad_perm:[2,3,0,1] row_mask:0xf bank_mask:0xf
	s_nop 1
	v_add_f32_dpp v2, v2, v2 row_half_mirror row_mask:0xf bank_mask:0xf
	s_nop 1
	v_add_f32_dpp v2, v2, v2 row_mirror row_mask:0xf bank_mask:0xf
	ds_bpermute_b32 v5, v213, v2
	s_waitcnt lgkmcnt(0)
	v_add_f32_e32 v2, v2, v5
	v_fmamk_f32 v2, v2, 0x3c000000, v233
	v_rsq_f32_e32 v2, v2
	s_nop 0
	v_mul_f32_e32 v1, v1, v2
	v_mul_f32_e32 v1, v89, v1
	v_cvt_pk_bf16_f32 v1, v1, v144
	ds_write_b16 v68, v1 offset:2720
	v_mul_f32_e32 v1, v4, v2
	v_mul_f32_e32 v1, v90, v1
	v_cvt_pk_bf16_f32 v1, v1, v144
	ds_write_b16 v68, v1 offset:2784
	v_mul_f32_e32 v1, v6, v2
	v_mul_f32_e32 v0, v0, v2
	v_mul_f32_e32 v1, v91, v1
	v_mul_f32_e32 v0, v85, v0
	v_cvt_pk_bf16_f32 v1, v1, v144
	ds_write_b16 v68, v1 offset:2848
	v_cvt_pk_bf16_f32 v0, v0, v144
	ds_write_b16 v68, v0 offset:2912
	v_rcp_f32_e32 v0, v67
	s_nop 0
	v_mul_f32_e32 v0, v84, v0
	v_fma_f32 v2, -v23, v0, v103
	v_fma_f32 v1, -v7, v0, v99
	v_mul_f32_e32 v4, v2, v2
	v_fmac_f32_e32 v4, v1, v1
	v_fma_f32 v5, -v39, v0, v107
	v_fmac_f32_e32 v4, v5, v5
	v_fma_f32 v0, -v55, v0, v111
	v_fmac_f32_e32 v4, v0, v0
	s_nop 1
	v_add_f32_dpp v3, v4, v4 quad_perm:[1,0,3,2] row_mask:0xf bank_mask:0xf
	s_nop 1
	v_add_f32_dpp v3, v3, v3 quad_perm:[2,3,0,1] row_mask:0xf bank_mask:0xf
	s_nop 1
	v_add_f32_dpp v3, v3, v3 row_half_mirror row_mask:0xf bank_mask:0xf
	s_nop 1
	v_add_f32_dpp v3, v3, v3 row_mirror row_mask:0xf bank_mask:0xf
	ds_bpermute_b32 v4, v213, v3
	s_waitcnt lgkmcnt(0)
; __device__ __forceinline__ unsigned cvtpk(float lo, float hi) { unsigned r; asm volatile("v_cvt_pk_bf16_f32 %0, %1, %2" : "=v"(r) : "v"(lo), "v"(hi)); return r; }
; template <bool GRPB> __device__ __forceinline__ void attn_pass(const float mbK, const float bmax2, const int pass, float* __restrict__ scr, bf16* __restrict__ mixrow, const float lam, const float* __restrict__ gsub, const float one_m_li, ...
;     ...
;       for (int i = 0; i < 4; ++i) { const float rl = __builtin_amdgcn_rcpf(lv[i]) * lam_; float dv[4]; float sq = 0.f;
; #pragma unroll
;         for (int d0 = 0; d0 < 4; ++d0) { dv[d0] = av[d0][i] - rl * o[d0][4 * r4 + i]; sq += dv[d0] * dv[d0]; }
;         sq += __shfl_xor(sq, 1); sq += __shfl_xor(sq, 2); sq += __shfl_xor(sq, 4); sq += __shfl_xor(sq, 8); sq += __shfl_xor(sq, 16);
;         const float rs = __builtin_amdgcn_rsqf(sq * (1.0f / 128.0f) + EPS);
;         unsigned short* orow = (unsigned short*)(ost_e + (8 * r4 + 4 * hi + i) * OST_PITCH) + r32;
; #pragma unroll
;         for (int d0 = 0; d0 < 4; ++d0) orow[d0 * 32] = (unsigned short)(cvtpk(dv[d0] * rs * g[d0], 0.f) & 0xffffu); } }
	v_add_f32_e32 v3, v3, v4
	v_fmamk_f32 v3, v3, 0x3c000000, v233
	v_rsq_f32_e32 v3, v3
	s_nop 0
	v_mul_f32_e32 v1, v1, v3
	v_mul_f32_e32 v1, v89, v1
	v_cvt_pk_bf16_f32 v1, v1, v144
	ds_write_b16 v68, v1 offset:2992
	v_mul_f32_e32 v1, v2, v3
	v_mul_f32_e32 v1, v90, v1
	v_cvt_pk_bf16_f32 v1, v1, v144
	ds_write_b16 v68, v1 offset:3056
	v_mul_f32_e32 v1, v5, v3
	v_mul_f32_e32 v0, v0, v3
	v_mul_f32_e32 v1, v91, v1
	v_mul_f32_e32 v0, v85, v0
	v_cvt_pk_bf16_f32 v1, v1, v144
	ds_write_b16 v68, v1 offset:3120
	v_cvt_pk_bf16_f32 v0, v0, v144
	ds_write_b16 v68, v0 offset:3184
	ds_read_b128 v[32:35], v92 offset:64
	s_waitcnt lgkmcnt(0)
	v_rcp_f32_e32 v32, v32
	s_nop 0
	v_mul_f32_e32 v32, v84, v32
	s_waitcnt vmcnt(7)
	v_fma_f32 v8, -v8, v32, v112
	s_waitcnt vmcnt(6)
	v_fma_f32 v16, -v24, v32, v116
	v_mul_f32_e32 v20, v16, v16
	v_fmac_f32_e32 v20, v8, v8
	s_waitcnt vmcnt(5)
	v_fma_f32 v4, -v40, v32, v120
	v_fmac_f32_e32 v20, v4, v4
	s_waitcnt vmcnt(4)
	v_fma_f32 v0, -v56, v32, v124
	v_fmac_f32_e32 v20, v0, v0
	ds_bpermute_b32 v24, v145, v20
	s_waitcnt lgkmcnt(0)
	v_add_f32_e32 v20, v20, v24
	ds_bpermute_b32 v24, v210, v20
	s_waitcnt lgkmcnt(0)
	v_add_f32_e32 v20, v20, v24
	ds_bpermute_b32 v24, v211, v20
	s_waitcnt lgkmcnt(0)
	v_add_f32_e32 v20, v20, v24
	ds_bpermute_b32 v24, v212, v20
	s_waitcnt lgkmcnt(0)
	v_add_f32_e32 v20, v20, v24
	ds_bpermute_b32 v24, v213, v20
	s_waitcnt lgkmcnt(0)
	v_add_f32_e32 v20, v20, v24
	v_fmamk_f32 v20, v20, 0x3c000000, v233
	v_rsq_f32_e32 v20, v20
	s_nop 0
	v_mul_f32_e32 v8, v8, v20
	v_mul_f32_e32 v8, v89, v8
	v_cvt_pk_bf16_f32 v8, v8, v144
	ds_write_b16 v68, v8 offset:4352
	v_mul_f32_e32 v8, v16, v20
	v_mul_f32_e32 v4, v4, v20
	v_mul_f32_e32 v0, v0, v20
	v_mul_f32_e32 v8, v90, v8
	v_mul_f32_e32 v4, v91, v4
	v_mul_f32_e32 v0, v85, v0
	v_cvt_pk_bf16_f32 v8, v8, v144
	ds_write_b16 v68, v8 offset:4416
	v_cvt_pk_bf16_f32 v4, v4, v144
	ds_write_b16 v68, v4 offset:4480
	v_cvt_pk_bf16_f32 v0, v0, v144
	ds_write_b16 v68, v0 offset:4544
	v_rcp_f32_e32 v0, v33
	s_nop 0
	v_mul_f32_e32 v0, v84, v0
	v_fma_f32 v8, -v25, v0, v117
	v_fma_f32 v4, -v9, v0, v113
	v_mul_f32_e32 v9, v8, v8
	v_fmac_f32_e32 v9, v4, v4
	v_fma_f32 v5, -v41, v0, v121
	v_fmac_f32_e32 v9, v5, v5
	v_fma_f32 v0, -v57, v0, v125
	v_fmac_f32_e32 v9, v0, v0
	s_nop 1
	v_add_f32_dpp v1, v9, v9 quad_perm:[1,0,3,2] row_mask:0xf bank_mask:0xf
	s_nop 1
	v_add_f32_dpp v1, v1, v1 quad_perm:[2,3,0,1] row_mask:0xf bank_mask:0xf
	s_nop 1
	v_add_f32_dpp v1, v1, v1 row_half_mirror row_mask:0xf bank_mask:0xf
	s_nop 1
	v_add_f32_dpp v1, v1, v1 row_mirror row_mask:0xf bank_mask:0xf
	ds_bpermute_b32 v9, v213, v1
	s_waitcnt lgkmcnt(0)
	v_add_f32_e32 v1, v1, v9
	v_fmamk_f32 v1, v1, 0x3c000000, v233
	v_rsq_f32_e32 v1, v1
	s_nop 0
	v_mul_f32_e32 v4, v4, v1
	v_mul_f32_e32 v4, v89, v4
	v_cvt_pk_bf16_f32 v4, v4, v144
	ds_write_b16 v68, v4 offset:4624
	v_mul_f32_e32 v4, v8, v1
	v_mul_f32_e32 v4, v90, v4
	v_cvt_pk_bf16_f32 v4, v4, v144
	ds_write_b16 v68, v4 offset:4688
	v_mul_f32_e32 v4, v5, v1
	v_mul_f32_e32 v0, v0, v1
	v_mul_f32_e32 v4, v91, v4
	v_mul_f32_e32 v0, v85, v0
	v_cvt_pk_bf16_f32 v4, v4, v144
	ds_write_b16 v68, v4 offset:4752
	v_cvt_pk_bf16_f32 v0, v0, v144
	ds_write_b16 v68, v0 offset:4816
	v_rcp_f32_e32 v0, v34
	s_nop 0
	v_mul_f32_e32 v0, v84, v0
	v_fma_f32 v4, -v26, v0, v118
	v_fma_f32 v1, -v10, v0, v114
	v_mul_f32_e32 v5, v4, v4
	v_fmac_f32_e32 v5, v1, v1
	v_fma_f32 v6, -v42, v0, v122
	v_fmac_f32_e32 v5, v6, v6
	v_fma_f32 v0, -v58, v0, v126
	v_fmac_f32_e32 v5, v0, v0
	s_nop 1
	v_add_f32_dpp v2, v5, v5 quad_perm:[1,0,3,2] row_mask:0xf bank_mask:0xf
	s_nop 1
	v_add_f32_dpp v2, v2, v2 quad_perm:[2,3,0,1] row_mask:0xf bank_mask:0xf
	s_nop 1
	v_add_f32_dpp v2, v2, v2 row_half_mirror row_mask:0xf bank_mask:0xf
	s_nop 1
	v_add_f32_dpp v2, v2, v2 row_mirror row_mask:0xf bank_mask:0xf
	ds_bpermute_b32 v5, v213, v2
	s_waitcnt lgkmcnt(0)
	v_add_f32_e32 v2, v2, v5
	v_fmamk_f32 v2, v2, 0x3c000000, v233
	v_rsq_f32_e32 v2, v2
	s_nop 0
	v_mul_f32_e32 v1, v1, v2
	v_mul_f32_e32 v1, v89, v1
	v_cvt_pk_bf16_f32 v1, v1, v144
	ds_write_b16 v68, v1 offset:4896
	v_mul_f32_e32 v1, v4, v2
	v_mul_f32_e32 v1, v90, v1
	v_cvt_pk_bf16_f32 v1, v1, v144
	ds_write_b16 v68, v1 offset:4960
	v_mul_f32_e32 v1, v6, v2
	v_mul_f32_e32 v0, v0, v2
	v_mul_f32_e32 v1, v91, v1
	v_mul_f32_e32 v0, v85, v0
	v_cvt_pk_bf16_f32 v1, v1, v144
	ds_write_b16 v68, v1 offset:5024
	v_cvt_pk_bf16_f32 v0, v0, v144
	ds_write_b16 v68, v0 offset:5088
	v_rcp_f32_e32 v0, v35
	s_nop 0
	v_mul_f32_e32 v0, v84, v0
	v_fma_f32 v2, -v27, v0, v119
	v_fma_f32 v1, -v11, v0, v115
	v_mul_f32_e32 v4, v2, v2
	v_fmac_f32_e32 v4, v1, v1
	v_fma_f32 v5, -v43, v0, v123
	v_fmac_f32_e32 v4, v5, v5
	v_fma_f32 v0, -v59, v0, v127
	v_fmac_f32_e32 v4, v0, v0
	s_nop 1
	v_add_f32_dpp v3, v4, v4 quad_perm:[1,0,3,2] row_mask:0xf bank_mask:0xf
	s_nop 1
	v_add_f32_dpp v3, v3, v3 quad_perm:[2,3,0,1] row_mask:0xf bank_mask:0xf
	s_nop 1
	v_add_f32_dpp v3, v3, v3 row_half_mirror row_mask:0xf bank_mask:0xf
	s_nop 1
	v_add_f32_dpp v3, v3, v3 row_mirror row_mask:0xf bank_mask:0xf
	ds_bpermute_b32 v4, v213, v3
	s_waitcnt lgkmcnt(0)
; __device__ __forceinline__ unsigned cvtpk(float lo, float hi) { unsigned r; asm volatile("v_cvt_pk_bf16_f32 %0, %1, %2" : "=v"(r) : "v"(lo), "v"(hi)); return r; }
; template <bool GRPB> __device__ __forceinline__ void attn_pass(const float mbK, const float bmax2, const int pass, float* __restrict__ scr, bf16* __restrict__ mixrow, const float lam, const float* __restrict__ gsub, const float one_m_li, ...
;     ...
;       for (int i = 0; i < 4; ++i) { const float rl = __builtin_amdgcn_rcpf(lv[i]) * lam_; float dv[4]; float sq = 0.f;
; #pragma unroll
;         for (int d0 = 0; d0 < 4; ++d0) { dv[d0] = av[d0][i] - rl * o[d0][4 * r4 + i]; sq += dv[d0] * dv[d0]; }
;         sq += __shfl_xor(sq, 1); sq += __shfl_xor(sq, 2); sq += __shfl_xor(sq, 4); sq += __shfl_xor(sq, 8); sq += __shfl_xor(sq, 16);
;         const float rs = __builtin_amdgcn_rsqf(sq * (1.0f / 128.0f) + EPS);
;         unsigned short* orow = (unsigned short*)(ost_e + (8 * r4 + 4 * hi + i) * OST_PITCH) + r32;
; #pragma unroll
;         for (int d0 = 0; d0 < 4; ++d0) orow[d0 * 32] = (unsigned short)(cvtpk(dv[d0] * rs * g[d0], 0.f) & 0xffffu); } }
;     asm volatile("s_waitcnt lgkmcnt(0)" ::: "memory");
	v_add_f32_e32 v3, v3, v4
	v_fmamk_f32 v3, v3, 0x3c000000, v233
	v_rsq_f32_e32 v3, v3
	s_nop 0
	v_mul_f32_e32 v1, v1, v3
	v_mul_f32_e32 v1, v89, v1
	v_cvt_pk_bf16_f32 v1, v1, v144
	ds_write_b16 v68, v1 offset:5168
	v_mul_f32_e32 v1, v2, v3
	v_mul_f32_e32 v1, v90, v1
	v_cvt_pk_bf16_f32 v1, v1, v144
	ds_write_b16 v68, v1 offset:5232
	v_mul_f32_e32 v1, v5, v3
	v_mul_f32_e32 v0, v0, v3
	v_mul_f32_e32 v1, v91, v1
	v_mul_f32_e32 v0, v85, v0
	v_cvt_pk_bf16_f32 v1, v1, v144
	ds_write_b16 v68, v1 offset:5296
	v_cvt_pk_bf16_f32 v0, v0, v144
	ds_write_b16 v68, v0 offset:5360
	ds_read_b128 v[20:23], v92 offset:96
	s_waitcnt lgkmcnt(0)
	v_rcp_f32_e32 v20, v20
	s_nop 0
	v_mul_f32_e32 v20, v84, v20
	s_waitcnt vmcnt(3)
	v_fma_f32 v8, -v12, v20, v128
	s_waitcnt vmcnt(2)
	v_fma_f32 v12, -v28, v20, v132
	v_mul_f32_e32 v16, v12, v12
	v_fmac_f32_e32 v16, v8, v8
	s_waitcnt vmcnt(1)
	v_fma_f32 v4, -v44, v20, v136
	v_fmac_f32_e32 v16, v4, v4
	s_waitcnt vmcnt(0)
	v_fma_f32 v0, -v60, v20, v140
	v_fmac_f32_e32 v16, v0, v0
	ds_bpermute_b32 v20, v145, v16
	s_waitcnt lgkmcnt(0)
	v_add_f32_e32 v16, v16, v20
	ds_bpermute_b32 v20, v210, v16
	s_waitcnt lgkmcnt(0)
	v_add_f32_e32 v16, v16, v20
	ds_bpermute_b32 v20, v211, v16
	s_waitcnt lgkmcnt(0)
	v_add_f32_e32 v16, v16, v20
	ds_bpermute_b32 v20, v212, v16
	s_waitcnt lgkmcnt(0)
	v_add_f32_e32 v16, v16, v20
	ds_bpermute_b32 v20, v213, v16
	s_waitcnt lgkmcnt(0)
	v_add_f32_e32 v16, v16, v20
	v_fmamk_f32 v16, v16, 0x3c000000, v233
	v_rsq_f32_e32 v16, v16
	s_nop 0
	v_mul_f32_e32 v8, v8, v16
	v_mul_f32_e32 v8, v89, v8
	v_cvt_pk_bf16_f32 v8, v8, v144
	ds_write_b16 v68, v8 offset:6528
	v_mul_f32_e32 v8, v12, v16
	v_mul_f32_e32 v4, v4, v16
	v_mul_f32_e32 v0, v0, v16
	v_mul_f32_e32 v8, v90, v8
	v_mul_f32_e32 v4, v91, v4
	v_mul_f32_e32 v0, v85, v0
	v_cvt_pk_bf16_f32 v8, v8, v144
	ds_write_b16 v68, v8 offset:6592
	v_cvt_pk_bf16_f32 v4, v4, v144
	ds_write_b16 v68, v4 offset:6656
	v_cvt_pk_bf16_f32 v0, v0, v144
	ds_write_b16 v68, v0 offset:6720
	v_rcp_f32_e32 v0, v21
	s_nop 0
	v_mul_f32_e32 v0, v84, v0
	v_fma_f32 v8, -v29, v0, v133
	v_fma_f32 v4, -v13, v0, v129
	v_mul_f32_e32 v9, v8, v8
	v_fmac_f32_e32 v9, v4, v4
	v_fma_f32 v5, -v45, v0, v137
	v_fmac_f32_e32 v9, v5, v5
	v_fma_f32 v0, -v61, v0, v141
	v_fmac_f32_e32 v9, v0, v0
	s_nop 1
	v_add_f32_dpp v1, v9, v9 quad_perm:[1,0,3,2] row_mask:0xf bank_mask:0xf
	s_nop 1
	v_add_f32_dpp v1, v1, v1 quad_perm:[2,3,0,1] row_mask:0xf bank_mask:0xf
	s_nop 1
	v_add_f32_dpp v1, v1, v1 row_half_mirror row_mask:0xf bank_mask:0xf
	s_nop 1
	v_add_f32_dpp v1, v1, v1 row_mirror row_mask:0xf bank_mask:0xf
	ds_bpermute_b32 v9, v213, v1
	s_waitcnt lgkmcnt(0)
	v_add_f32_e32 v1, v1, v9
	v_fmamk_f32 v1, v1, 0x3c000000, v233
	v_rsq_f32_e32 v1, v1
	s_nop 0
	v_mul_f32_e32 v4, v4, v1
	v_mul_f32_e32 v4, v89, v4
	v_cvt_pk_bf16_f32 v4, v4, v144
	ds_write_b16 v68, v4 offset:6800
	v_mul_f32_e32 v4, v8, v1
	v_mul_f32_e32 v4, v90, v4
	v_cvt_pk_bf16_f32 v4, v4, v144
	ds_write_b16 v68, v4 offset:6864
	v_mul_f32_e32 v4, v5, v1
	v_mul_f32_e32 v0, v0, v1
	v_mul_f32_e32 v4, v91, v4
	v_mul_f32_e32 v0, v85, v0
	v_cvt_pk_bf16_f32 v4, v4, v144
	ds_write_b16 v68, v4 offset:6928
	v_cvt_pk_bf16_f32 v0, v0, v144
	ds_write_b16 v68, v0 offset:6992
	v_rcp_f32_e32 v0, v22
	s_nop 0
	v_mul_f32_e32 v0, v84, v0
	v_fma_f32 v4, -v30, v0, v134
	v_fma_f32 v1, -v14, v0, v130
	v_mul_f32_e32 v5, v4, v4
	v_fmac_f32_e32 v5, v1, v1
	v_fma_f32 v6, -v46, v0, v138
	v_fmac_f32_e32 v5, v6, v6
	v_fma_f32 v0, -v62, v0, v142
	v_fmac_f32_e32 v5, v0, v0
	s_nop 1
	v_add_f32_dpp v2, v5, v5 quad_perm:[1,0,3,2] row_mask:0xf bank_mask:0xf
	s_nop 1
	v_add_f32_dpp v2, v2, v2 quad_perm:[2,3,0,1] row_mask:0xf bank_mask:0xf
	s_nop 1
	v_add_f32_dpp v2, v2, v2 row_half_mirror row_mask:0xf bank_mask:0xf
	s_nop 1
	v_add_f32_dpp v2, v2, v2 row_mirror row_mask:0xf bank_mask:0xf
	ds_bpermute_b32 v5, v213, v2
	s_waitcnt lgkmcnt(0)
	v_add_f32_e32 v2, v2, v5
	v_fmamk_f32 v2, v2, 0x3c000000, v233
	v_rsq_f32_e32 v2, v2
	s_nop 0
	v_mul_f32_e32 v1, v1, v2
	v_mul_f32_e32 v1, v89, v1
	v_cvt_pk_bf16_f32 v1, v1, v144
	ds_write_b16 v68, v1 offset:7072
	v_mul_f32_e32 v1, v4, v2
	v_mul_f32_e32 v1, v90, v1
	v_cvt_pk_bf16_f32 v1, v1, v144
	ds_write_b16 v68, v1 offset:7136
	v_mul_f32_e32 v1, v6, v2
	v_mul_f32_e32 v0, v0, v2
	v_mul_f32_e32 v1, v91, v1
	v_mul_f32_e32 v0, v85, v0
	v_cvt_pk_bf16_f32 v1, v1, v144
	ds_write_b16 v68, v1 offset:7200
	v_cvt_pk_bf16_f32 v0, v0, v144
	ds_write_b16 v68, v0 offset:7264
	v_rcp_f32_e32 v0, v23
	s_nop 0
	v_mul_f32_e32 v0, v84, v0
	v_fma_f32 v2, -v31, v0, v135
	v_fma_f32 v1, -v15, v0, v131
	v_mul_f32_e32 v4, v2, v2
	v_fmac_f32_e32 v4, v1, v1
	v_fma_f32 v5, -v47, v0, v139
	v_fmac_f32_e32 v4, v5, v5
	v_fma_f32 v0, -v63, v0, v143
	v_fmac_f32_e32 v4, v0, v0
	s_nop 1
	v_add_f32_dpp v3, v4, v4 quad_perm:[1,0,3,2] row_mask:0xf bank_mask:0xf
	s_nop 1
	v_add_f32_dpp v3, v3, v3 quad_perm:[2,3,0,1] row_mask:0xf bank_mask:0xf
	s_nop 1
	v_add_f32_dpp v3, v3, v3 row_half_mirror row_mask:0xf bank_mask:0xf
	s_nop 1
	v_add_f32_dpp v3, v3, v3 row_mirror row_mask:0xf bank_mask:0xf
	ds_bpermute_b32 v4, v213, v3
	s_waitcnt lgkmcnt(0)
	v_add_f32_e32 v3, v3, v4
	v_fmamk_f32 v3, v3, 0x3c000000, v233
	v_rsq_f32_e32 v3, v3
	s_nop 0
	v_mul_f32_e32 v1, v1, v3
	v_mul_f32_e32 v1, v89, v1
	v_cvt_pk_bf16_f32 v1, v1, v144
	ds_write_b16 v68, v1 offset:7344
	v_mul_f32_e32 v1, v2, v3
	v_mul_f32_e32 v1, v90, v1
	v_cvt_pk_bf16_f32 v1, v1, v144
	ds_write_b16 v68, v1 offset:7408
	v_mul_f32_e32 v1, v5, v3
	v_mul_f32_e32 v0, v0, v3
	v_mul_f32_e32 v1, v91, v1
	v_mul_f32_e32 v0, v85, v0
	v_cvt_pk_bf16_f32 v1, v1, v144
	ds_write_b16 v68, v1 offset:7472
	v_cvt_pk_bf16_f32 v0, v0, v144
	ds_write_b16 v68, v0 offset:7536
	s_waitcnt lgkmcnt(0)

; __device__ __forceinline__ unsigned cvtpk(float lo, float hi) { unsigned r; asm volatile("v_cvt_pk_bf16_f32 %0, %1, %2" : "=v"(r) : "v"(lo), "v"(hi)); return r; }
; template <bool GRPB> __device__ __forceinline__ void attn_pass(const float mbK, const float bmax2, const int pass, float* __restrict__ scr, bf16* __restrict__ mixrow, const float lam, const float* __restrict__ gsub, const float one_m_li, ...
;     ...
;     float g[4];
;     const float lam_ = *(const float*)(lds + 147328), oml_ = *(const float*)(lds + 147332);
; #pragma unroll
;     for (int d0 = 0; d0 < 4; ++d0) g[d0] = gsub[d0 * 32 + r32] * oml_;
; #pragma unroll
;     for (int r4 = 0; r4 < 4; ++r4) { const f32x4 lv = *(const f32x4*)(li_e + 8 * r4 + 4 * hi);
;       f32x4 av[4];
; #pragma unroll
;       for (int d0 = 0; d0 < 4; ++d0) av[d0] = scr4[d0 * 4 + r4];
; #pragma unroll
;       for (int i = 0; i < 4; ++i) { const float rl = __builtin_amdgcn_rcpf(lv[i]) * lam_; float dv[4]; float sq = 0.f;
; #pragma unroll
;         for (int d0 = 0; d0 < 4; ++d0) { dv[d0] = av[d0][i] - rl * o[d0][4 * r4 + i]; sq += dv[d0] * dv[d0]; }
;         sq += __shfl_xor(sq, 1); sq += __shfl_xor(sq, 2); sq += __shfl_xor(sq, 4); sq += __shfl_xor(sq, 8); sq += __shfl_xor(sq, 16);
;         const float rs = __builtin_amdgcn_rsqf(sq * (1.0f / 128.0f) + EPS);
;         unsigned short* orow = (unsigned short*)(ost_e + (8 * r4 + 4 * hi + i) * OST_PITCH) + r32;
; #pragma unroll
;         for (int d0 = 0; d0 < 4; ++d0) orow[d0 * 32] = (unsigned short)(cvtpk(dv[d0] * rs * g[d0], 0.f) & 0xffffu); } }
.LBB0_346:
	s_or_b64 exec, exec, s[0:1]
	v_lshrrev_b32_e32 v64, 6, v67
	s_movk_i32 s0, 0x2200
	v_mul_lo_u32 v88, v64, s0
	v_readlane_b32 s0, v254, 41
	v_ashrrev_i32_e32 v147, 31, v146
	v_lshlrev_b64 v[64:65], 8, v[146:147]
	v_add_u32_e32 v93, s0, v88
	v_readlane_b32 s0, v254, 37
	s_waitcnt lgkmcnt(0)
	v_lshl_add_u64 v[86:87], s[40:41], 0, v[64:65]
	v_add_u32_e32 v92, v66, v200
	v_mov_b32_e32 v64, s0
	ds_read_b64 v[84:85], v64
	ds_read_b128 v[80:83], v92
	v_lshlrev_b32_e32 v64, 2, v218
	global_load_dword v168, v64, s[42:43]
	global_load_dword v169, v64, s[42:43] offset:128
	global_load_dword v170, v64, s[42:43] offset:256
	global_load_dword v171, v64, s[42:43] offset:384
	v_lshlrev_b32_e32 v94, 1, v218
	s_mov_b64 s[0:1], 0
	s_waitcnt lgkmcnt(0)
	v_rcp_f32_e32 v80, v80
	s_waitcnt vmcnt(0)
	v_mul_f32_e32 v89, v85, v168
	v_mul_f32_e32 v80, v84, v80
	v_mul_f32_e32 v90, v85, v169
	v_mul_f32_e32 v91, v85, v170
	v_mul_f32_e32 v85, v85, v171
	global_load_dwordx4 v[76:79], v[86:87], off
	global_load_dwordx4 v[72:75], v[86:87], off offset:64
	global_load_dwordx4 v[68:71], v[86:87], off offset:128
	global_load_dwordx4 v[64:67], v[86:87], off offset:192
	global_load_dwordx4 v[96:99], v[86:87], off offset:16
	global_load_dwordx4 v[100:103], v[86:87], off offset:80
	global_load_dwordx4 v[104:107], v[86:87], off offset:144
	global_load_dwordx4 v[108:111], v[86:87], off offset:208
	global_load_dwordx4 v[112:115], v[86:87], off offset:32
	global_load_dwordx4 v[116:119], v[86:87], off offset:96
	global_load_dwordx4 v[120:123], v[86:87], off offset:160
	global_load_dwordx4 v[124:127], v[86:87], off offset:224
	global_load_dwordx4 v[128:131], v[86:87], off offset:48
	global_load_dwordx4 v[132:135], v[86:87], off offset:112
	global_load_dwordx4 v[136:139], v[86:87], off offset:176
	global_load_dwordx4 v[140:143], v[86:87], off offset:240
	s_waitcnt vmcnt(15)
	v_fma_f32 v0, -v0, v80, v76
	s_waitcnt vmcnt(14)
	v_fma_f32 v16, -v16, v80, v72
	v_mul_f32_e32 v72, v16, v16
	v_fmac_f32_e32 v72, v0, v0
	s_waitcnt vmcnt(13)
	v_fma_f32 v32, -v32, v80, v68
	v_fmac_f32_e32 v72, v32, v32
	s_waitcnt vmcnt(12)
	v_fma_f32 v48, -v48, v80, v64
	v_fmac_f32_e32 v72, v48, v48
	s_nop 1
	v_add_f32_dpp v64, v72, v72 quad_perm:[1,0,3,2] row_mask:0xf bank_mask:0xf
	s_nop 1
	v_add_f32_dpp v64, v64, v64 quad_perm:[2,3,0,1] row_mask:0xf bank_mask:0xf
	s_nop 1
	v_add_f32_dpp v64, v64, v64 row_half_mirror row_mask:0xf bank_mask:0xf
	s_nop 1
	v_add_f32_dpp v64, v64, v64 row_mirror row_mask:0xf bank_mask:0xf
	ds_bpermute_b32 v68, v213, v64
	s_waitcnt lgkmcnt(0)
	v_add_f32_e32 v64, v64, v68
	v_fmamk_f32 v64, v64, 0x3c000000, v233
	v_rsq_f32_e32 v64, v64
	v_mul_u32_u24_e32 v68, 0x440, v217
	v_add3_u32 v68, v93, v94, v68
	v_mul_f32_e32 v0, v0, v64
	v_mul_f32_e32 v0, v89, v0
	v_cvt_pk_bf16_f32 v0, v0, v144
	ds_write_b16 v68, v0
	v_mul_f32_e32 v0, v16, v64
	v_mul_f32_e32 v0, v90, v0
	v_cvt_pk_bf16_f32 v0, v0, v144
	ds_write_b16 v68, v0 offset:64
	v_mul_f32_e32 v0, v32, v64
	v_mul_f32_e32 v0, v91, v0
	v_cvt_pk_bf16_f32 v0, v0, v144
	ds_write_b16 v68, v0 offset:128
	v_mul_f32_e32 v0, v48, v64
	v_mul_f32_e32 v0, v85, v0
	v_cvt_pk_bf16_f32 v0, v0, v144
	ds_write_b16 v68, v0 offset:192
	v_rcp_f32_e32 v0, v81
	s_nop 0
	v_mul_f32_e32 v0, v84, v0
	v_fma_f32 v16, -v17, v0, v73
	v_fma_f32 v1, -v1, v0, v77
	v_mul_f32_e32 v17, v16, v16
	v_fmac_f32_e32 v17, v1, v1
	v_fma_f32 v32, -v33, v0, v69
	v_fmac_f32_e32 v17, v32, v32
	v_fma_f32 v0, -v49, v0, v65
	v_fmac_f32_e32 v17, v0, v0
	ds_bpermute_b32 v33, v145, v17
	s_waitcnt lgkmcnt(0)
	v_add_f32_e32 v17, v17, v33
	ds_bpermute_b32 v33, v210, v17
	s_waitcnt lgkmcnt(0)
	v_add_f32_e32 v17, v17, v33
	ds_bpermute_b32 v33, v211, v17
	s_waitcnt lgkmcnt(0)
	v_add_f32_e32 v17, v17, v33
	ds_bpermute_b32 v33, v212, v17
	s_waitcnt lgkmcnt(0)
	v_add_f32_e32 v17, v17, v33
	ds_bpermute_b32 v33, v213, v17
	s_waitcnt lgkmcnt(0)
	v_add_f32_e32 v17, v17, v33
	v_fmamk_f32 v17, v17, 0x3c000000, v233
	v_rsq_f32_e32 v17, v17
	s_nop 0
	v_mul_f32_e32 v1, v1, v17
	v_mul_f32_e32 v1, v89, v1
	v_cvt_pk_bf16_f32 v1, v1, v144
	ds_write_b16 v68, v1 offset:272
	v_mul_f32_e32 v1, v16, v17
	v_mul_f32_e32 v1, v90, v1
	v_cvt_pk_bf16_f32 v1, v1, v144
	ds_write_b16 v68, v1 offset:336
	v_mul_f32_e32 v1, v32, v17
	v_mul_f32_e32 v0, v0, v17
	v_mul_f32_e32 v1, v91, v1
	v_mul_f32_e32 v0, v85, v0
	v_cvt_pk_bf16_f32 v1, v1, v144
	ds_write_b16 v68, v1 offset:400
	v_cvt_pk_bf16_f32 v0, v0, v144
	ds_write_b16 v68, v0 offset:464
	v_rcp_f32_e32 v0, v82
	s_nop 0
	v_mul_f32_e32 v0, v84, v0
	v_fma_f32 v1, -v2, v0, v78
	v_fma_f32 v2, -v18, v0, v74
	v_mul_f32_e32 v16, v2, v2
	v_fmac_f32_e32 v16, v1, v1
	v_fma_f32 v17, -v34, v0, v70
	v_fmac_f32_e32 v16, v17, v17
	v_fma_f32 v0, -v50, v0, v66
	v_fmac_f32_e32 v16, v0, v0
	ds_bpermute_b32 v18, v145, v16
	s_waitcnt lgkmcnt(0)
	v_add_f32_e32 v16, v16, v18
	ds_bpermute_b32 v18, v210, v16
	s_waitcnt lgkmcnt(0)
	v_add_f32_e32 v16, v16, v18
	ds_bpermute_b32 v18, v211, v16
	s_waitcnt lgkmcnt(0)
	v_add_f32_e32 v16, v16, v18
	ds_bpermute_b32 v18, v212, v16
	s_waitcnt lgkmcnt(0)
	v_add_f32_e32 v16, v16, v18
	ds_bpermute_b32 v18, v213, v16
	s_waitcnt lgkmcnt(0)
	v_add_f32_e32 v16, v16, v18
	v_fmamk_f32 v16, v16, 0x3c000000, v233
	v_rsq_f32_e32 v16, v16
	s_nop 0
	v_mul_f32_e32 v1, v1, v16
	v_mul_f32_e32 v1, v89, v1
	v_cvt_pk_bf16_f32 v1, v1, v144
	ds_write_b16 v68, v1 offset:544
	v_mul_f32_e32 v1, v2, v16
	v_mul_f32_e32 v1, v90, v1
	v_cvt_pk_bf16_f32 v1, v1, v144
	ds_write_b16 v68, v1 offset:608
	v_mul_f32_e32 v1, v17, v16
	v_mul_f32_e32 v0, v0, v16
	v_mul_f32_e32 v1, v91, v1
	v_mul_f32_e32 v0, v85, v0
	v_cvt_pk_bf16_f32 v1, v1, v144
	ds_write_b16 v68, v1 offset:672
	v_cvt_pk_bf16_f32 v0, v0, v144
	ds_write_b16 v68, v0 offset:736
	v_rcp_f32_e32 v0, v83
	s_nop 0
	v_mul_f32_e32 v0, v84, v0
	v_fma_f32 v2, -v19, v0, v75
	v_fma_f32 v1, -v3, v0, v79
	v_mul_f32_e32 v3, v2, v2
	v_fmac_f32_e32 v3, v1, v1
	v_fma_f32 v16, -v35, v0, v71
	v_fmac_f32_e32 v3, v16, v16
	v_fma_f32 v0, -v51, v0, v67
	v_fmac_f32_e32 v3, v0, v0
	ds_bpermute_b32 v17, v145, v3
	s_waitcnt lgkmcnt(0)
; __device__ __forceinline__ unsigned cvtpk(float lo, float hi) { unsigned r; asm volatile("v_cvt_pk_bf16_f32 %0, %1, %2" : "=v"(r) : "v"(lo), "v"(hi)); return r; }
; template <bool GRPB> __device__ __forceinline__ void attn_pass(const float mbK, const float bmax2, const int pass, float* __restrict__ scr, bf16* __restrict__ mixrow, const float lam, const float* __restrict__ gsub, const float one_m_li, ...
;     ...
;       for (int i = 0; i < 4; ++i) { const float rl = __builtin_amdgcn_rcpf(lv[i]) * lam_; float dv[4]; float sq = 0.f;
; #pragma unroll
;         for (int d0 = 0; d0 < 4; ++d0) { dv[d0] = av[d0][i] - rl * o[d0][4 * r4 + i]; sq += dv[d0] * dv[d0]; }
;         sq += __shfl_xor(sq, 1); sq += __shfl_xor(sq, 2); sq += __shfl_xor(sq, 4); sq += __shfl_xor(sq, 8); sq += __shfl_xor(sq, 16);
;         const float rs = __builtin_amdgcn_rsqf(sq * (1.0f / 128.0f) + EPS);
;         unsigned short* orow = (unsigned short*)(ost_e + (8 * r4 + 4 * hi + i) * OST_PITCH) + r32;
; #pragma unroll
;         for (int d0 = 0; d0 < 4; ++d0) orow[d0 * 32] = (unsigned short)(cvtpk(dv[d0] * rs * g[d0], 0.f) & 0xffffu); } }
	v_add_f32_e32 v3, v3, v17
	ds_bpermute_b32 v17, v210, v3
	s_waitcnt lgkmcnt(0)
	v_add_f32_e32 v3, v3, v17
	ds_bpermute_b32 v17, v211, v3
	s_waitcnt lgkmcnt(0)
	v_add_f32_e32 v3, v3, v17
	ds_bpermute_b32 v17, v212, v3
	s_waitcnt lgkmcnt(0)
	v_add_f32_e32 v3, v3, v17
	ds_bpermute_b32 v17, v213, v3
	s_waitcnt lgkmcnt(0)
	v_add_f32_e32 v3, v3, v17
	v_fmamk_f32 v3, v3, 0x3c000000, v233
	v_rsq_f32_e32 v3, v3
	s_nop 0
	v_mul_f32_e32 v1, v1, v3
	v_mul_f32_e32 v1, v89, v1
	v_cvt_pk_bf16_f32 v1, v1, v144
	ds_write_b16 v68, v1 offset:816
	v_mul_f32_e32 v1, v2, v3
	v_mul_f32_e32 v1, v90, v1
	v_cvt_pk_bf16_f32 v1, v1, v144
	ds_write_b16 v68, v1 offset:880
	v_mul_f32_e32 v1, v16, v3
	v_mul_f32_e32 v0, v0, v3
	v_mul_f32_e32 v1, v91, v1
	v_mul_f32_e32 v0, v85, v0
	v_cvt_pk_bf16_f32 v1, v1, v144
	ds_write_b16 v68, v1 offset:944
	v_cvt_pk_bf16_f32 v0, v0, v144
	ds_write_b16 v68, v0 offset:1008
	ds_read_b128 v[64:67], v92 offset:32
	s_waitcnt lgkmcnt(0)
	v_rcp_f32_e32 v64, v64
	s_nop 0
	v_mul_f32_e32 v64, v84, v64
	s_waitcnt vmcnt(11)
	v_fma_f32 v4, -v4, v64, v96
	s_waitcnt vmcnt(10)
	v_fma_f32 v20, -v20, v64, v100
	v_mul_f32_e32 v32, v20, v20
	v_fmac_f32_e32 v32, v4, v4
	s_waitcnt vmcnt(9)
	v_fma_f32 v16, -v36, v64, v104
	v_fmac_f32_e32 v32, v16, v16
	s_waitcnt vmcnt(8)
	v_fma_f32 v0, -v52, v64, v108
	v_fmac_f32_e32 v32, v0, v0
	ds_bpermute_b32 v36, v145, v32
	s_waitcnt lgkmcnt(0)
	v_add_f32_e32 v32, v32, v36
	ds_bpermute_b32 v36, v210, v32
	s_waitcnt lgkmcnt(0)
	v_add_f32_e32 v32, v32, v36
	ds_bpermute_b32 v36, v211, v32
	s_waitcnt lgkmcnt(0)
	v_add_f32_e32 v32, v32, v36
	ds_bpermute_b32 v36, v212, v32
	s_waitcnt lgkmcnt(0)
	v_add_f32_e32 v32, v32, v36
	ds_bpermute_b32 v36, v213, v32
	s_waitcnt lgkmcnt(0)
	v_add_f32_e32 v32, v32, v36
	v_fmamk_f32 v32, v32, 0x3c000000, v233
	v_rsq_f32_e32 v32, v32
	s_nop 0
	v_mul_f32_e32 v4, v4, v32
	v_mul_f32_e32 v4, v89, v4
	v_cvt_pk_bf16_f32 v4, v4, v144
	ds_write_b16 v68, v4 offset:2176
	v_mul_f32_e32 v4, v20, v32
	v_mul_f32_e32 v4, v90, v4
	v_cvt_pk_bf16_f32 v4, v4, v144
	ds_write_b16 v68, v4 offset:2240
	v_mul_f32_e32 v4, v16, v32
	v_mul_f32_e32 v0, v0, v32
	v_mul_f32_e32 v4, v91, v4
	v_mul_f32_e32 v0, v85, v0
	v_cvt_pk_bf16_f32 v4, v4, v144
	ds_write_b16 v68, v4 offset:2304
	v_cvt_pk_bf16_f32 v0, v0, v144
	ds_write_b16 v68, v0 offset:2368
	v_rcp_f32_e32 v0, v65
	s_nop 0
	v_mul_f32_e32 v0, v84, v0
	v_fma_f32 v4, -v5, v0, v97
	v_fma_f32 v5, -v21, v0, v101
	v_mul_f32_e32 v16, v5, v5
	v_fmac_f32_e32 v16, v4, v4
	v_fma_f32 v17, -v37, v0, v105
	v_fmac_f32_e32 v16, v17, v17
	v_fma_f32 v0, -v53, v0, v109
	v_fmac_f32_e32 v16, v0, v0
	s_nop 1
	v_add_f32_dpp v1, v16, v16 quad_perm:[1,0,3,2] row_mask:0xf bank_mask:0xf
	s_nop 1
	v_add_f32_dpp v1, v1, v1 quad_perm:[2,3,0,1] row_mask:0xf bank_mask:0xf
	s_nop 1
	v_add_f32_dpp v1, v1, v1 row_half_mirror row_mask:0xf bank_mask:0xf
	s_nop 1
	v_add_f32_dpp v1, v1, v1 row_mirror row_mask:0xf bank_mask:0xf
	ds_bpermute_b32 v16, v213, v1
	s_waitcnt lgkmcnt(0)
	v_add_f32_e32 v1, v1, v16
	v_fmamk_f32 v1, v1, 0x3c000000, v233
	v_rsq_f32_e32 v1, v1
	s_nop 0
	v_mul_f32_e32 v4, v4, v1
	v_mul_f32_e32 v4, v89, v4
	v_cvt_pk_bf16_f32 v4, v4, v144
	ds_write_b16 v68, v4 offset:2448
	v_mul_f32_e32 v4, v5, v1
	v_mul_f32_e32 v4, v90, v4
	v_cvt_pk_bf16_f32 v4, v4, v144
	ds_write_b16 v68, v4 offset:2512
	v_mul_f32_e32 v4, v17, v1
	v_mul_f32_e32 v0, v0, v1
	v_mul_f32_e32 v4, v91, v4
	v_mul_f32_e32 v0, v85, v0
	v_cvt_pk_bf16_f32 v4, v4, v144
	ds_write_b16 v68, v4 offset:2576
	v_cvt_pk_bf16_f32 v0, v0, v144
	ds_write_b16 v68, v0 offset:2640
	v_rcp_f32_e32 v0, v66
	s_nop 0
	v_mul_f32_e32 v0, v84, v0
	v_fma_f32 v4, -v22, v0, v102
	v_fma_f32 v1, -v6, v0, v98
	v_mul_f32_e32 v5, v4, v4
	v_fmac_f32_e32 v5, v1, v1
	v_fma_f32 v6, -v38, v0, v106
	v_fmac_f32_e32 v5, v6, v6
	v_fma_f32 v0, -v54, v0, v110
	v_fmac_f32_e32 v5, v0, v0
	s_nop 1
	v_add_f32_dpp v2, v5, v5 quad_perm:[1,0,3,2] row_mask:0xf bank_mask:0xf
	s_nop 1
	v_add_f32_dpp v2, v2, v2 quad_perm:[2,3,0,1] row_mask:0xf bank_mask:0xf
	s_nop 1
	v_add_f32_dpp v2, v2, v2 row_half_mirror row_mask:0xf bank_mask:0xf
	s_nop 1
	v_add_f32_dpp v2, v2, v2 row_mirror row_mask:0xf bank_mask:0xf
	ds_bpermute_b32 v5, v213, v2
	s_waitcnt lgkmcnt(0)
	v_add_f32_e32 v2, v2, v5
	v_fmamk_f32 v2, v2, 0x3c000000, v233
	v_rsq_f32_e32 v2, v2
	s_nop 0
	v_mul_f32_e32 v1, v1, v2
	v_mul_f32_e32 v1, v89, v1
	v_cvt_pk_bf16_f32 v1, v1, v144
	ds_write_b16 v68, v1 offset:2720
	v_mul_f32_e32 v1, v4, v2
	v_mul_f32_e32 v1, v90, v1
	v_cvt_pk_bf16_f32 v1, v1, v144
	ds_write_b16 v68, v1 offset:2784
	v_mul_f32_e32 v1, v6, v2
	v_mul_f32_e32 v0, v0, v2
	v_mul_f32_e32 v1, v91, v1
	v_mul_f32_e32 v0, v85, v0
	v_cvt_pk_bf16_f32 v1, v1, v144
	ds_write_b16 v68, v1 offset:2848
	v_cvt_pk_bf16_f32 v0, v0, v144
	ds_write_b16 v68, v0 offset:2912
	v_rcp_f32_e32 v0, v67
	s_nop 0
	v_mul_f32_e32 v0, v84, v0
	v_fma_f32 v2, -v23, v0, v103
	v_fma_f32 v1, -v7, v0, v99
	v_mul_f32_e32 v4, v2, v2
	v_fmac_f32_e32 v4, v1, v1
	v_fma_f32 v5, -v39, v0, v107
	v_fmac_f32_e32 v4, v5, v5
	v_fma_f32 v0, -v55, v0, v111
	v_fmac_f32_e32 v4, v0, v0
	s_nop 1
	v_add_f32_dpp v3, v4, v4 quad_perm:[1,0,3,2] row_mask:0xf bank_mask:0xf
	s_nop 1
	v_add_f32_dpp v3, v3, v3 quad_perm:[2,3,0,1] row_mask:0xf bank_mask:0xf
	s_nop 1
	v_add_f32_dpp v3, v3, v3 row_half_mirror row_mask:0xf bank_mask:0xf
	s_nop 1
	v_add_f32_dpp v3, v3, v3 row_mirror row_mask:0xf bank_mask:0xf
	ds_bpermute_b32 v4, v213, v3
	s_waitcnt lgkmcnt(0)
; __device__ __forceinline__ unsigned cvtpk(float lo, float hi) { unsigned r; asm volatile("v_cvt_pk_bf16_f32 %0, %1, %2" : "=v"(r) : "v"(lo), "v"(hi)); return r; }
; template <bool GRPB> __device__ __forceinline__ void attn_pass(const float mbK, const float bmax2, const int pass, float* __restrict__ scr, bf16* __restrict__ mixrow, const float lam, const float* __restrict__ gsub, const float one_m_li, ...
;     ...
;       for (int i = 0; i < 4; ++i) { const float rl = __builtin_amdgcn_rcpf(lv[i]) * lam_; float dv[4]; float sq = 0.f;
; #pragma unroll
;         for (int d0 = 0; d0 < 4; ++d0) { dv[d0] = av[d0][i] - rl * o[d0][4 * r4 + i]; sq += dv[d0] * dv[d0]; }
;         sq += __shfl_xor(sq, 1); sq += __shfl_xor(sq, 2); sq += __shfl_xor(sq, 4); sq += __shfl_xor(sq, 8); sq += __shfl_xor(sq, 16);
;         const float rs = __builtin_amdgcn_rsqf(sq * (1.0f / 128.0f) + EPS);
;         unsigned short* orow = (unsigned short*)(ost_e + (8 * r4 + 4 * hi + i) * OST_PITCH) + r32;
; #pragma unroll
;         for (int d0 = 0; d0 < 4; ++d0) orow[d0 * 32] = (unsigned short)(cvtpk(dv[d0] * rs * g[d0], 0.f) & 0xffffu); } }
	v_add_f32_e32 v3, v3, v4
	v_fmamk_f32 v3, v3, 0x3c000000, v233
	v_rsq_f32_e32 v3, v3
	s_nop 0
	v_mul_f32_e32 v1, v1, v3
	v_mul_f32_e32 v1, v89, v1
	v_cvt_pk_bf16_f32 v1, v1, v144
	ds_write_b16 v68, v1 offset:2992
	v_mul_f32_e32 v1, v2, v3
	v_mul_f32_e32 v1, v90, v1
	v_cvt_pk_bf16_f32 v1, v1, v144
	ds_write_b16 v68, v1 offset:3056
	v_mul_f32_e32 v1, v5, v3
	v_mul_f32_e32 v0, v0, v3
	v_mul_f32_e32 v1, v91, v1
	v_mul_f32_e32 v0, v85, v0
	v_cvt_pk_bf16_f32 v1, v1, v144
	ds_write_b16 v68, v1 offset:3120
	v_cvt_pk_bf16_f32 v0, v0, v144
	ds_write_b16 v68, v0 offset:3184
	ds_read_b128 v[32:35], v92 offset:64
	s_waitcnt lgkmcnt(0)
	v_rcp_f32_e32 v32, v32
	s_nop 0
	v_mul_f32_e32 v32, v84, v32
	s_waitcnt vmcnt(7)
	v_fma_f32 v8, -v8, v32, v112
	s_waitcnt vmcnt(6)
	v_fma_f32 v16, -v24, v32, v116
	v_mul_f32_e32 v20, v16, v16
	v_fmac_f32_e32 v20, v8, v8
	s_waitcnt vmcnt(5)
	v_fma_f32 v4, -v40, v32, v120
	v_fmac_f32_e32 v20, v4, v4
	s_waitcnt vmcnt(4)
	v_fma_f32 v0, -v56, v32, v124
	v_fmac_f32_e32 v20, v0, v0
	ds_bpermute_b32 v24, v145, v20
	s_waitcnt lgkmcnt(0)
	v_add_f32_e32 v20, v20, v24
	ds_bpermute_b32 v24, v210, v20
	s_waitcnt lgkmcnt(0)
	v_add_f32_e32 v20, v20, v24
	ds_bpermute_b32 v24, v211, v20
	s_waitcnt lgkmcnt(0)
	v_add_f32_e32 v20, v20, v24
	ds_bpermute_b32 v24, v212, v20
	s_waitcnt lgkmcnt(0)
	v_add_f32_e32 v20, v20, v24
	ds_bpermute_b32 v24, v213, v20
	s_waitcnt lgkmcnt(0)
	v_add_f32_e32 v20, v20, v24
	v_fmamk_f32 v20, v20, 0x3c000000, v233
	v_rsq_f32_e32 v20, v20
	s_nop 0
	v_mul_f32_e32 v8, v8, v20
	v_mul_f32_e32 v8, v89, v8
	v_cvt_pk_bf16_f32 v8, v8, v144
	ds_write_b16 v68, v8 offset:4352
	v_mul_f32_e32 v8, v16, v20
	v_mul_f32_e32 v4, v4, v20
	v_mul_f32_e32 v0, v0, v20
	v_mul_f32_e32 v8, v90, v8
	v_mul_f32_e32 v4, v91, v4
	v_mul_f32_e32 v0, v85, v0
	v_cvt_pk_bf16_f32 v8, v8, v144
	ds_write_b16 v68, v8 offset:4416
	v_cvt_pk_bf16_f32 v4, v4, v144
	ds_write_b16 v68, v4 offset:4480
	v_cvt_pk_bf16_f32 v0, v0, v144
	ds_write_b16 v68, v0 offset:4544
	v_rcp_f32_e32 v0, v33
	s_nop 0
	v_mul_f32_e32 v0, v84, v0
	v_fma_f32 v8, -v25, v0, v117
	v_fma_f32 v4, -v9, v0, v113
	v_mul_f32_e32 v9, v8, v8
	v_fmac_f32_e32 v9, v4, v4
	v_fma_f32 v5, -v41, v0, v121
	v_fmac_f32_e32 v9, v5, v5
	v_fma_f32 v0, -v57, v0, v125
	v_fmac_f32_e32 v9, v0, v0
	s_nop 1
	v_add_f32_dpp v1, v9, v9 quad_perm:[1,0,3,2] row_mask:0xf bank_mask:0xf
	s_nop 1
	v_add_f32_dpp v1, v1, v1 quad_perm:[2,3,0,1] row_mask:0xf bank_mask:0xf
	s_nop 1
	v_add_f32_dpp v1, v1, v1 row_half_mirror row_mask:0xf bank_mask:0xf
	s_nop 1
	v_add_f32_dpp v1, v1, v1 row_mirror row_mask:0xf bank_mask:0xf
	ds_bpermute_b32 v9, v213, v1
	s_waitcnt lgkmcnt(0)
	v_add_f32_e32 v1, v1, v9
	v_fmamk_f32 v1, v1, 0x3c000000, v233
	v_rsq_f32_e32 v1, v1
	s_nop 0
	v_mul_f32_e32 v4, v4, v1
	v_mul_f32_e32 v4, v89, v4
	v_cvt_pk_bf16_f32 v4, v4, v144
	ds_write_b16 v68, v4 offset:4624
	v_mul_f32_e32 v4, v8, v1
	v_mul_f32_e32 v4, v90, v4
	v_cvt_pk_bf16_f32 v4, v4, v144
	ds_write_b16 v68, v4 offset:4688
	v_mul_f32_e32 v4, v5, v1
	v_mul_f32_e32 v0, v0, v1
	v_mul_f32_e32 v4, v91, v4
	v_mul_f32_e32 v0, v85, v0
	v_cvt_pk_bf16_f32 v4, v4, v144
	ds_write_b16 v68, v4 offset:4752
	v_cvt_pk_bf16_f32 v0, v0, v144
	ds_write_b16 v68, v0 offset:4816
	v_rcp_f32_e32 v0, v34
	s_nop 0
	v_mul_f32_e32 v0, v84, v0
	v_fma_f32 v4, -v26, v0, v118
	v_fma_f32 v1, -v10, v0, v114
	v_mul_f32_e32 v5, v4, v4
	v_fmac_f32_e32 v5, v1, v1
	v_fma_f32 v6, -v42, v0, v122
	v_fmac_f32_e32 v5, v6, v6
	v_fma_f32 v0, -v58, v0, v126
	v_fmac_f32_e32 v5, v0, v0
	s_nop 1
	v_add_f32_dpp v2, v5, v5 quad_perm:[1,0,3,2] row_mask:0xf bank_mask:0xf
	s_nop 1
	v_add_f32_dpp v2, v2, v2 quad_perm:[2,3,0,1] row_mask:0xf bank_mask:0xf
	s_nop 1
	v_add_f32_dpp v2, v2, v2 row_half_mirror row_mask:0xf bank_mask:0xf
	s_nop 1
	v_add_f32_dpp v2, v2, v2 row_mirror row_mask:0xf bank_mask:0xf
	ds_bpermute_b32 v5, v213, v2
	s_waitcnt lgkmcnt(0)
	v_add_f32_e32 v2, v2, v5
	v_fmamk_f32 v2, v2, 0x3c000000, v233
	v_rsq_f32_e32 v2, v2
	s_nop 0
	v_mul_f32_e32 v1, v1, v2
	v_mul_f32_e32 v1, v89, v1
	v_cvt_pk_bf16_f32 v1, v1, v144
	ds_write_b16 v68, v1 offset:4896
	v_mul_f32_e32 v1, v4, v2
	v_mul_f32_e32 v1, v90, v1
	v_cvt_pk_bf16_f32 v1, v1, v144
	ds_write_b16 v68, v1 offset:4960
	v_mul_f32_e32 v1, v6, v2
	v_mul_f32_e32 v0, v0, v2
	v_mul_f32_e32 v1, v91, v1
	v_mul_f32_e32 v0, v85, v0
	v_cvt_pk_bf16_f32 v1, v1, v144
	ds_write_b16 v68, v1 offset:5024
	v_cvt_pk_bf16_f32 v0, v0, v144
	ds_write_b16 v68, v0 offset:5088
	v_rcp_f32_e32 v0, v35
	s_nop 0
	v_mul_f32_e32 v0, v84, v0
	v_fma_f32 v2, -v27, v0, v119
	v_fma_f32 v1, -v11, v0, v115
	v_mul_f32_e32 v4, v2, v2
	v_fmac_f32_e32 v4, v1, v1
	v_fma_f32 v5, -v43, v0, v123
	v_fmac_f32_e32 v4, v5, v5
	v_fma_f32 v0, -v59, v0, v127
	v_fmac_f32_e32 v4, v0, v0
	s_nop 1
	v_add_f32_dpp v3, v4, v4 quad_perm:[1,0,3,2] row_mask:0xf bank_mask:0xf
	s_nop 1
	v_add_f32_dpp v3, v3, v3 quad_perm:[2,3,0,1] row_mask:0xf bank_mask:0xf
	s_nop 1
	v_add_f32_dpp v3, v3, v3 row_half_mirror row_mask:0xf bank_mask:0xf
	s_nop 1
	v_add_f32_dpp v3, v3, v3 row_mirror row_mask:0xf bank_mask:0xf
	ds_bpermute_b32 v4, v213, v3
	s_waitcnt lgkmcnt(0)
; __device__ __forceinline__ unsigned cvtpk(float lo, float hi) { unsigned r; asm volatile("v_cvt_pk_bf16_f32 %0, %1, %2" : "=v"(r) : "v"(lo), "v"(hi)); return r; }
; template <bool GRPB> __device__ __forceinline__ void attn_pass(const float mbK, const float bmax2, const int pass, float* __restrict__ scr, bf16* __restrict__ mixrow, const float lam, const float* __restrict__ gsub, const float one_m_li, ...
;     ...
;       for (int i = 0; i < 4; ++i) { const float rl = __builtin_amdgcn_rcpf(lv[i]) * lam_; float dv[4]; float sq = 0.f;
; #pragma unroll
;         for (int d0 = 0; d0 < 4; ++d0) { dv[d0] = av[d0][i] - rl * o[d0][4 * r4 + i]; sq += dv[d0] * dv[d0]; }
;         sq += __shfl_xor(sq, 1); sq += __shfl_xor(sq, 2); sq += __shfl_xor(sq, 4); sq += __shfl_xor(sq, 8); sq += __shfl_xor(sq, 16);
;         const float rs = __builtin_amdgcn_rsqf(sq * (1.0f / 128.0f) + EPS);
;         unsigned short* orow = (unsigned short*)(ost_e + (8 * r4 + 4 * hi + i) * OST_PITCH) + r32;
; #pragma unroll
;         for (int d0 = 0; d0 < 4; ++d0) orow[d0 * 32] = (unsigned short)(cvtpk(dv[d0] * rs * g[d0], 0.f) & 0xffffu); } }
;     asm volatile("s_waitcnt lgkmcnt(0)" ::: "memory");
	v_add_f32_e32 v3, v3, v4
	v_fmamk_f32 v3, v3, 0x3c000000, v233
	v_rsq_f32_e32 v3, v3
	s_nop 0
	v_mul_f32_e32 v1, v1, v3
	v_mul_f32_e32 v1, v89, v1
	v_cvt_pk_bf16_f32 v1, v1, v144
	ds_write_b16 v68, v1 offset:5168
	v_mul_f32_e32 v1, v2, v3
	v_mul_f32_e32 v1, v90, v1
	v_cvt_pk_bf16_f32 v1, v1, v144
	ds_write_b16 v68, v1 offset:5232
	v_mul_f32_e32 v1, v5, v3
	v_mul_f32_e32 v0, v0, v3
	v_mul_f32_e32 v1, v91, v1
	v_mul_f32_e32 v0, v85, v0
	v_cvt_pk_bf16_f32 v1, v1, v144
	ds_write_b16 v68, v1 offset:5296
	v_cvt_pk_bf16_f32 v0, v0, v144
	ds_write_b16 v68, v0 offset:5360
	ds_read_b128 v[20:23], v92 offset:96
	s_waitcnt lgkmcnt(0)
	v_rcp_f32_e32 v20, v20
	s_nop 0
	v_mul_f32_e32 v20, v84, v20
	s_waitcnt vmcnt(3)
	v_fma_f32 v8, -v12, v20, v128
	s_waitcnt vmcnt(2)
	v_fma_f32 v12, -v28, v20, v132
	v_mul_f32_e32 v16, v12, v12
	v_fmac_f32_e32 v16, v8, v8
	s_waitcnt vmcnt(1)
	v_fma_f32 v4, -v44, v20, v136
	v_fmac_f32_e32 v16, v4, v4
	s_waitcnt vmcnt(0)
	v_fma_f32 v0, -v60, v20, v140
	v_fmac_f32_e32 v16, v0, v0
	ds_bpermute_b32 v20, v145, v16
	s_waitcnt lgkmcnt(0)
	v_add_f32_e32 v16, v16, v20
	ds_bpermute_b32 v20, v210, v16
	s_waitcnt lgkmcnt(0)
	v_add_f32_e32 v16, v16, v20
	ds_bpermute_b32 v20, v211, v16
	s_waitcnt lgkmcnt(0)
	v_add_f32_e32 v16, v16, v20
	ds_bpermute_b32 v20, v212, v16
	s_waitcnt lgkmcnt(0)
	v_add_f32_e32 v16, v16, v20
	ds_bpermute_b32 v20, v213, v16
	s_waitcnt lgkmcnt(0)
	v_add_f32_e32 v16, v16, v20
	v_fmamk_f32 v16, v16, 0x3c000000, v233
	v_rsq_f32_e32 v16, v16
	s_nop 0
	v_mul_f32_e32 v8, v8, v16
	v_mul_f32_e32 v8, v89, v8
	v_cvt_pk_bf16_f32 v8, v8, v144
	ds_write_b16 v68, v8 offset:6528
	v_mul_f32_e32 v8, v12, v16
	v_mul_f32_e32 v4, v4, v16
	v_mul_f32_e32 v0, v0, v16
	v_mul_f32_e32 v8, v90, v8
	v_mul_f32_e32 v4, v91, v4
	v_mul_f32_e32 v0, v85, v0
	v_cvt_pk_bf16_f32 v8, v8, v144
	ds_write_b16 v68, v8 offset:6592
	v_cvt_pk_bf16_f32 v4, v4, v144
	ds_write_b16 v68, v4 offset:6656
	v_cvt_pk_bf16_f32 v0, v0, v144
	ds_write_b16 v68, v0 offset:6720
	v_rcp_f32_e32 v0, v21
	s_nop 0
	v_mul_f32_e32 v0, v84, v0
	v_fma_f32 v8, -v29, v0, v133
	v_fma_f32 v4, -v13, v0, v129
	v_mul_f32_e32 v9, v8, v8
	v_fmac_f32_e32 v9, v4, v4
	v_fma_f32 v5, -v45, v0, v137
	v_fmac_f32_e32 v9, v5, v5
	v_fma_f32 v0, -v61, v0, v141
	v_fmac_f32_e32 v9, v0, v0
	s_nop 1
	v_add_f32_dpp v1, v9, v9 quad_perm:[1,0,3,2] row_mask:0xf bank_mask:0xf
	s_nop 1
	v_add_f32_dpp v1, v1, v1 quad_perm:[2,3,0,1] row_mask:0xf bank_mask:0xf
	s_nop 1
	v_add_f32_dpp v1, v1, v1 row_half_mirror row_mask:0xf bank_mask:0xf
	s_nop 1
	v_add_f32_dpp v1, v1, v1 row_mirror row_mask:0xf bank_mask:0xf
	ds_bpermute_b32 v9, v213, v1
	s_waitcnt lgkmcnt(0)
	v_add_f32_e32 v1, v1, v9
	v_fmamk_f32 v1, v1, 0x3c000000, v233
	v_rsq_f32_e32 v1, v1
	s_nop 0
	v_mul_f32_e32 v4, v4, v1
	v_mul_f32_e32 v4, v89, v4
	v_cvt_pk_bf16_f32 v4, v4, v144
	ds_write_b16 v68, v4 offset:6800
	v_mul_f32_e32 v4, v8, v1
	v_mul_f32_e32 v4, v90, v4
	v_cvt_pk_bf16_f32 v4, v4, v144
	ds_write_b16 v68, v4 offset:6864
	v_mul_f32_e32 v4, v5, v1
	v_mul_f32_e32 v0, v0, v1
	v_mul_f32_e32 v4, v91, v4
	v_mul_f32_e32 v0, v85, v0
	v_cvt_pk_bf16_f32 v4, v4, v144
	ds_write_b16 v68, v4 offset:6928
	v_cvt_pk_bf16_f32 v0, v0, v144
	ds_write_b16 v68, v0 offset:6992
	v_rcp_f32_e32 v0, v22
	s_nop 0
	v_mul_f32_e32 v0, v84, v0
	v_fma_f32 v4, -v30, v0, v134
	v_fma_f32 v1, -v14, v0, v130
	v_mul_f32_e32 v5, v4, v4
	v_fmac_f32_e32 v5, v1, v1
	v_fma_f32 v6, -v46, v0, v138
	v_fmac_f32_e32 v5, v6, v6
	v_fma_f32 v0, -v62, v0, v142
	v_fmac_f32_e32 v5, v0, v0
	s_nop 1
	v_add_f32_dpp v2, v5, v5 quad_perm:[1,0,3,2] row_mask:0xf bank_mask:0xf
	s_nop 1
	v_add_f32_dpp v2, v2, v2 quad_perm:[2,3,0,1] row_mask:0xf bank_mask:0xf
	s_nop 1
	v_add_f32_dpp v2, v2, v2 row_half_mirror row_mask:0xf bank_mask:0xf
	s_nop 1
	v_add_f32_dpp v2, v2, v2 row_mirror row_mask:0xf bank_mask:0xf
	ds_bpermute_b32 v5, v213, v2
	s_waitcnt lgkmcnt(0)
	v_add_f32_e32 v2, v2, v5
	v_fmamk_f32 v2, v2, 0x3c000000, v233
	v_rsq_f32_e32 v2, v2
	s_nop 0
	v_mul_f32_e32 v1, v1, v2
	v_mul_f32_e32 v1, v89, v1
	v_cvt_pk_bf16_f32 v1, v1, v144
	ds_write_b16 v68, v1 offset:7072
	v_mul_f32_e32 v1, v4, v2
	v_mul_f32_e32 v1, v90, v1
	v_cvt_pk_bf16_f32 v1, v1, v144
	ds_write_b16 v68, v1 offset:7136
	v_mul_f32_e32 v1, v6, v2
	v_mul_f32_e32 v0, v0, v2
	v_mul_f32_e32 v1, v91, v1
	v_mul_f32_e32 v0, v85, v0
	v_cvt_pk_bf16_f32 v1, v1, v144
	ds_write_b16 v68, v1 offset:7200
	v_cvt_pk_bf16_f32 v0, v0, v144
	ds_write_b16 v68, v0 offset:7264
	v_rcp_f32_e32 v0, v23
	s_nop 0
	v_mul_f32_e32 v0, v84, v0
	v_fma_f32 v2, -v31, v0, v135
	v_fma_f32 v1, -v15, v0, v131
	v_mul_f32_e32 v4, v2, v2
	v_fmac_f32_e32 v4, v1, v1
	v_fma_f32 v5, -v47, v0, v139
	v_fmac_f32_e32 v4, v5, v5
	v_fma_f32 v0, -v63, v0, v143
	v_fmac_f32_e32 v4, v0, v0
	s_nop 1
	v_add_f32_dpp v3, v4, v4 quad_perm:[1,0,3,2] row_mask:0xf bank_mask:0xf
	s_nop 1
	v_add_f32_dpp v3, v3, v3 quad_perm:[2,3,0,1] row_mask:0xf bank_mask:0xf
	s_nop 1
	v_add_f32_dpp v3, v3, v3 row_half_mirror row_mask:0xf bank_mask:0xf
	s_nop 1
	v_add_f32_dpp v3, v3, v3 row_mirror row_mask:0xf bank_mask:0xf
	ds_bpermute_b32 v4, v213, v3
	s_waitcnt lgkmcnt(0)
	v_add_f32_e32 v3, v3, v4
	v_fmamk_f32 v3, v3, 0x3c000000, v233
	v_rsq_f32_e32 v3, v3
	s_nop 0
	v_mul_f32_e32 v1, v1, v3
	v_mul_f32_e32 v1, v89, v1
	v_cvt_pk_bf16_f32 v1, v1, v144
	ds_write_b16 v68, v1 offset:7344
	v_mul_f32_e32 v1, v2, v3
	v_mul_f32_e32 v1, v90, v1
	v_cvt_pk_bf16_f32 v1, v1, v144
	ds_write_b16 v68, v1 offset:7408
	v_mul_f32_e32 v1, v5, v3
	v_mul_f32_e32 v0, v0, v3
	v_mul_f32_e32 v1, v91, v1
	v_mul_f32_e32 v0, v85, v0
	v_cvt_pk_bf16_f32 v1, v1, v144
	ds_write_b16 v68, v1 offset:7472
	v_cvt_pk_bf16_f32 v0, v0, v144
	ds_write_b16 v68, v0 offset:7536
	s_waitcnt lgkmcnt(0)
